# gemm_out: the peeled K step ahead of the K loop also reads its LDS fragments several ahead into spare VGPR quads (counted lgkmcnt), on top of the gemm_out loop and gemm_in last-step changes
# baseline (speedup 1.0000x reference)
.LBB0_60:
	s_or_b64 exec, exec, s[10:11]
	v_mov_b32_e32 v2, s8
	s_waitcnt lgkmcnt(0)
	s_barrier
	ds_read_b32 v2, v2
	s_waitcnt lgkmcnt(0)
	v_readfirstlane_b32 s2, v2
	s_ashr_i32 s10, s2, 3
	s_and_b32 s10, s10, -8
	s_or_b32 s12, s10, s48
	s_cmp_gt_i32 s12, 39
	s_mov_b64 s[10:11], -1
	s_cbranch_scc1 .LBB0_55
	s_lshl_b32 s11, s2, 7
	s_lshl_b32 s10, s12, 10
	s_and_b32 s11, s11, 0x380
	s_or_b32 s13, s10, s11
	s_bfe_u32 s12, s2, 0x30003
	s_lshl_b32 s49, s12, 7
	s_mul_i32 s10, s13, 0x1820
	s_mul_hi_i32 s2, s13, 0x1820
	s_add_u32 s10, s34, s10
	s_addc_u32 s11, s35, s2
	s_lshl_b32 s2, s12, 18
	v_readlane_b32 s42, v246, 23
	s_add_u32 s42, s42, s2
	v_readlane_b32 s43, v246, 24
	v_readfirstlane_b32 s56, v1
	v_add_u32_e32 v6, 0x4000, v1
	s_waitcnt lgkmcnt(0)
	s_barrier
	s_addc_u32 s43, s43, 0
	v_lshl_add_u64 v[2:3], v[66:67], 1, s[10:11]
	s_mov_b32 m0, s56
	v_readfirstlane_b32 s57, v6
	v_add_u32_e32 v8, 0x1000, v1
	global_load_lds_dwordx4 v[2:3], off
	v_lshl_add_u64 v[4:5], v[68:69], 1, s[42:43]
	s_mov_b32 m0, s57
	v_readfirstlane_b32 s58, v8
	v_add_u32_e32 v10, 0x5000, v1
	global_load_lds_dwordx4 v[4:5], off
	v_lshl_add_u64 v[6:7], v[70:71], 1, s[10:11]
	s_mov_b32 m0, s58
	v_readfirstlane_b32 s59, v10
	v_add_u32_e32 v12, 0x2000, v1
	global_load_lds_dwordx4 v[6:7], off
	v_lshl_add_u64 v[8:9], v[72:73], 1, s[42:43]
	s_mov_b32 m0, s59
	v_readfirstlane_b32 s60, v12
	v_add_u32_e32 v14, 0x6000, v1
	global_load_lds_dwordx4 v[8:9], off
	v_lshl_add_u64 v[10:11], v[74:75], 1, s[10:11]
	s_mov_b32 m0, s60
	v_readfirstlane_b32 s61, v14
	v_add_u32_e32 v16, 0x3000, v1
	global_load_lds_dwordx4 v[10:11], off
	v_lshl_add_u64 v[12:13], v[76:77], 1, s[42:43]
	s_mov_b32 m0, s61
	v_readfirstlane_b32 s97, v16
	v_add_u32_e32 v18, 0x7000, v1
	global_load_lds_dwordx4 v[12:13], off
	v_lshl_add_u64 v[14:15], v[78:79], 1, s[10:11]
	s_mov_b32 m0, s97
	v_readfirstlane_b32 s44, v18
	global_load_lds_dwordx4 v[14:15], off
	v_lshl_add_u64 v[16:17], v[80:81], 1, s[42:43]
	s_mov_b32 m0, s44
	v_add_u32_e32 v20, 0x8000, v1
	global_load_lds_dwordx4 v[16:17], off
	s_waitcnt vmcnt(0)
	v_readfirstlane_b32 s42, v20
	v_add_u32_e32 v20, 0xc000, v1
	s_waitcnt lgkmcnt(0)
	s_barrier
	v_lshl_add_u64 v[18:19], v[2:3], 0, s[98:99]
	s_mov_b32 m0, s42
	v_readfirstlane_b32 s43, v20
	v_add_u32_e32 v20, 0x9000, v1
	global_load_lds_dwordx4 v[18:19], off
	v_lshl_add_u64 v[18:19], v[4:5], 0, s[98:99]
	s_mov_b32 m0, s43
	v_readfirstlane_b32 s50, v20
	v_add_u32_e32 v20, 0xd000, v1
	global_load_lds_dwordx4 v[18:19], off
	v_lshl_add_u64 v[18:19], v[6:7], 0, s[98:99]
	s_mov_b32 m0, s50
	v_readfirstlane_b32 s51, v20
	v_add_u32_e32 v20, 0xa000, v1
	global_load_lds_dwordx4 v[18:19], off
	v_lshl_add_u64 v[18:19], v[8:9], 0, s[98:99]
	s_mov_b32 m0, s51
	v_readfirstlane_b32 s52, v20
	v_add_u32_e32 v20, 0xe000, v1
	global_load_lds_dwordx4 v[18:19], off
	v_lshl_add_u64 v[18:19], v[10:11], 0, s[98:99]
	s_mov_b32 m0, s52
	v_readfirstlane_b32 s53, v20
	v_add_u32_e32 v20, 0xb000, v1
	global_load_lds_dwordx4 v[18:19], off
	v_lshl_add_u64 v[18:19], v[12:13], 0, s[98:99]
	s_mov_b32 m0, s53
	v_readfirstlane_b32 s54, v20
	v_add_u32_e32 v20, 0xf000, v1
	global_load_lds_dwordx4 v[18:19], off
	v_lshl_add_u64 v[18:19], v[14:15], 0, s[98:99]
	s_mov_b32 m0, s54
	v_readfirstlane_b32 s55, v20
	global_load_lds_dwordx4 v[18:19], off
	v_lshl_add_u64 v[18:19], v[16:17], 0, s[98:99]
	s_mov_b32 m0, s55
	s_mov_b64 vcc, 0x100
	global_load_lds_dwordx4 v[18:19], off
	v_add_u32_e32 v19, v102, v104
	ds_read_b128 v[20:23], v19 offset:16384
	ds_read_b128 v[32:35], v19 offset:18432
	ds_read_b128 v[40:43], v19 offset:20480
	ds_read_b128 v[126:129], v19 offset:19456
	ds_read_b128 v[48:51], v19 offset:22528
	ds_read_b128 v[130:133], v19 offset:21504
	v_add_u32_e32 v18, v102, v103
	ds_read_b128 v[24:27], v18
	ds_read_b128 v[52:55], v18 offset:2048
	ds_read_b128 v[98:101], v18 offset:4096
	ds_read_b128 v[118:121], v18 offset:6144
	ds_read_b128 v[122:125], v19 offset:17408
	ds_read_b128 v[134:137], v19 offset:23552
	s_waitcnt lgkmcnt(0)
	v_mfma_f32_16x16x32_bf16 v[28:31], v[20:23], v[24:27], 0
	v_lshl_add_u64 v[64:65], v[2:3], 0, vcc
	s_mov_b32 m0, s56
	s_mov_b64 s[62:63], 0x180
	v_mfma_f32_16x16x32_bf16 v[36:39], v[32:35], v[24:27], 0
	v_mfma_f32_16x16x32_bf16 v[44:47], v[40:43], v[24:27], 0
	v_mfma_f32_16x16x32_bf16 v[24:27], v[48:51], v[24:27], 0
	v_mfma_f32_16x16x32_bf16 v[56:59], v[20:23], v[52:55], 0
	v_mfma_f32_16x16x32_bf16 v[60:63], v[32:35], v[52:55], 0
	v_mfma_f32_16x16x32_bf16 v[94:97], v[40:43], v[52:55], 0
	v_mfma_f32_16x16x32_bf16 v[52:55], v[48:51], v[52:55], 0
	v_mfma_f32_16x16x32_bf16 v[106:109], v[20:23], v[98:101], 0
	v_mfma_f32_16x16x32_bf16 v[110:113], v[32:35], v[98:101], 0
	v_mfma_f32_16x16x32_bf16 v[114:117], v[40:43], v[98:101], 0
	v_mfma_f32_16x16x32_bf16 v[98:101], v[48:51], v[98:101], 0
	v_mfma_f32_16x16x32_bf16 v[20:23], v[20:23], v[118:121], 0
	v_mfma_f32_16x16x32_bf16 v[32:35], v[32:35], v[118:121], 0
	v_mfma_f32_16x16x32_bf16 v[40:43], v[40:43], v[118:121], 0
	v_mfma_f32_16x16x32_bf16 v[48:51], v[48:51], v[118:121], 0
	ds_read_b128 v[118:121], v18 offset:1024
	s_waitcnt lgkmcnt(0)
	v_mfma_f32_16x16x32_bf16 v[28:31], v[122:125], v[118:121], v[28:31]
	v_mfma_f32_16x16x32_bf16 v[36:39], v[126:129], v[118:121], v[36:39]
	v_mfma_f32_16x16x32_bf16 v[44:47], v[130:133], v[118:121], v[44:47]
	v_mfma_f32_16x16x32_bf16 v[24:27], v[134:137], v[118:121], v[24:27]
	ds_read_b128 v[118:121], v18 offset:3072
	s_waitcnt lgkmcnt(0)
	v_mfma_f32_16x16x32_bf16 v[56:59], v[122:125], v[118:121], v[56:59]
	v_mfma_f32_16x16x32_bf16 v[60:63], v[126:129], v[118:121], v[60:63]
	v_mfma_f32_16x16x32_bf16 v[94:97], v[130:133], v[118:121], v[94:97]
	v_mfma_f32_16x16x32_bf16 v[52:55], v[134:137], v[118:121], v[52:55]
	ds_read_b128 v[118:121], v18 offset:5120
	s_waitcnt lgkmcnt(0)
	v_mfma_f32_16x16x32_bf16 v[106:109], v[122:125], v[118:121], v[106:109]
	v_mfma_f32_16x16x32_bf16 v[110:113], v[126:129], v[118:121], v[110:113]
	v_mfma_f32_16x16x32_bf16 v[114:117], v[130:133], v[118:121], v[114:117]
	v_mfma_f32_16x16x32_bf16 v[98:101], v[134:137], v[118:121], v[98:101]
	ds_read_b128 v[118:121], v18 offset:7168
	s_waitcnt vmcnt(0)
	s_waitcnt lgkmcnt(0)
	s_barrier
	global_load_lds_dwordx4 v[64:65], off
	v_lshl_add_u64 v[64:65], v[4:5], 0, vcc
	s_mov_b32 m0, s57
	s_waitcnt lgkmcnt(0)
	v_mfma_f32_16x16x32_bf16 v[20:23], v[122:125], v[118:121], v[20:23]
	global_load_lds_dwordx4 v[64:65], off
	v_lshl_add_u64 v[64:65], v[6:7], 0, vcc
	s_mov_b32 m0, s58
	v_mfma_f32_16x16x32_bf16 v[32:35], v[126:129], v[118:121], v[32:35]
	global_load_lds_dwordx4 v[64:65], off
	v_lshl_add_u64 v[64:65], v[8:9], 0, vcc
	s_mov_b32 m0, s59
	v_mfma_f32_16x16x32_bf16 v[40:43], v[130:133], v[118:121], v[40:43]
	global_load_lds_dwordx4 v[64:65], off
	v_lshl_add_u64 v[64:65], v[10:11], 0, vcc
	s_mov_b32 m0, s60
	v_mfma_f32_16x16x32_bf16 v[48:51], v[134:137], v[118:121], v[48:51]
	global_load_lds_dwordx4 v[64:65], off
	v_lshl_add_u64 v[64:65], v[12:13], 0, vcc
	s_mov_b32 m0, s61
	s_nop 0
	global_load_lds_dwordx4 v[64:65], off
	v_lshl_add_u64 v[64:65], v[14:15], 0, vcc
	s_mov_b32 m0, s97
	s_nop 0
	global_load_lds_dwordx4 v[64:65], off
	v_lshl_add_u64 v[64:65], v[16:17], 0, vcc
	s_mov_b32 m0, s44
	s_nop 0
	global_load_lds_dwordx4 v[64:65], off
	ds_read_b128 v[122:125], v19 offset:49152
	ds_read_b128 v[118:121], v18 offset:32768
	ds_read_b128 v[126:129], v19 offset:51200
	ds_read_b128 v[130:133], v19 offset:53248
	ds_read_b128 v[134:137], v19 offset:55296
	s_waitcnt lgkmcnt(0)
	v_mfma_f32_16x16x32_bf16 v[28:31], v[122:125], v[118:121], v[28:31]
	v_lshl_add_u64 v[64:65], v[2:3], 0, s[62:63]
	s_mov_b32 m0, s42
	v_mfma_f32_16x16x32_bf16 v[36:39], v[126:129], v[118:121], v[36:39]
	v_mfma_f32_16x16x32_bf16 v[44:47], v[130:133], v[118:121], v[44:47]
	v_mfma_f32_16x16x32_bf16 v[24:27], v[134:137], v[118:121], v[24:27]
	ds_read_b128 v[118:121], v18 offset:34816
	s_waitcnt lgkmcnt(0)
	v_mfma_f32_16x16x32_bf16 v[56:59], v[122:125], v[118:121], v[56:59]
	v_mfma_f32_16x16x32_bf16 v[60:63], v[126:129], v[118:121], v[60:63]
	v_mfma_f32_16x16x32_bf16 v[94:97], v[130:133], v[118:121], v[94:97]
	v_mfma_f32_16x16x32_bf16 v[52:55], v[134:137], v[118:121], v[52:55]
	ds_read_b128 v[118:121], v18 offset:36864
	s_waitcnt lgkmcnt(0)
	v_mfma_f32_16x16x32_bf16 v[106:109], v[122:125], v[118:121], v[106:109]
	v_mfma_f32_16x16x32_bf16 v[110:113], v[126:129], v[118:121], v[110:113]
	v_mfma_f32_16x16x32_bf16 v[114:117], v[130:133], v[118:121], v[114:117]
	v_mfma_f32_16x16x32_bf16 v[98:101], v[134:137], v[118:121], v[98:101]
	ds_read_b128 v[118:121], v18 offset:38912
	s_waitcnt lgkmcnt(0)
	v_mfma_f32_16x16x32_bf16 v[20:23], v[122:125], v[118:121], v[20:23]
	ds_read_b128 v[122:125], v19 offset:50176
	v_mfma_f32_16x16x32_bf16 v[32:35], v[126:129], v[118:121], v[32:35]
	ds_read_b128 v[126:129], v19 offset:52224
	v_mfma_f32_16x16x32_bf16 v[40:43], v[130:133], v[118:121], v[40:43]
	ds_read_b128 v[130:133], v19 offset:54272
	v_mfma_f32_16x16x32_bf16 v[48:51], v[134:137], v[118:121], v[48:51]
	ds_read_b128 v[134:137], v19 offset:56320
	ds_read_b128 v[118:121], v18 offset:33792
	s_waitcnt lgkmcnt(0)
	v_mfma_f32_16x16x32_bf16 v[28:31], v[122:125], v[118:121], v[28:31]
	v_mfma_f32_16x16x32_bf16 v[36:39], v[126:129], v[118:121], v[36:39]
	v_mfma_f32_16x16x32_bf16 v[44:47], v[130:133], v[118:121], v[44:47]
	v_mfma_f32_16x16x32_bf16 v[24:27], v[134:137], v[118:121], v[24:27]
	ds_read_b128 v[118:121], v18 offset:35840
	s_waitcnt lgkmcnt(0)
	v_mfma_f32_16x16x32_bf16 v[56:59], v[122:125], v[118:121], v[56:59]
	v_mfma_f32_16x16x32_bf16 v[60:63], v[126:129], v[118:121], v[60:63]
	v_mfma_f32_16x16x32_bf16 v[94:97], v[130:133], v[118:121], v[94:97]
	v_mfma_f32_16x16x32_bf16 v[52:55], v[134:137], v[118:121], v[52:55]
	ds_read_b128 v[118:121], v18 offset:37888
	s_waitcnt lgkmcnt(0)
	v_mfma_f32_16x16x32_bf16 v[106:109], v[122:125], v[118:121], v[106:109]
	v_mfma_f32_16x16x32_bf16 v[110:113], v[126:129], v[118:121], v[110:113]
	v_mfma_f32_16x16x32_bf16 v[114:117], v[130:133], v[118:121], v[114:117]
	v_mfma_f32_16x16x32_bf16 v[98:101], v[134:137], v[118:121], v[98:101]
	ds_read_b128 v[118:121], v18 offset:39936
	s_waitcnt vmcnt(0)
	s_waitcnt lgkmcnt(0)
	s_barrier
	global_load_lds_dwordx4 v[64:65], off
	v_lshl_add_u64 v[64:65], v[4:5], 0, s[62:63]
	s_mov_b32 m0, s43
	s_waitcnt lgkmcnt(0)
	v_mfma_f32_16x16x32_bf16 v[20:23], v[122:125], v[118:121], v[20:23]
	global_load_lds_dwordx4 v[64:65], off
	v_lshl_add_u64 v[64:65], v[6:7], 0, s[62:63]
	s_mov_b32 m0, s50
	v_mfma_f32_16x16x32_bf16 v[32:35], v[126:129], v[118:121], v[32:35]
	global_load_lds_dwordx4 v[64:65], off
	v_lshl_add_u64 v[64:65], v[8:9], 0, s[62:63]
	s_mov_b32 m0, s51
	v_mfma_f32_16x16x32_bf16 v[40:43], v[130:133], v[118:121], v[40:43]
	global_load_lds_dwordx4 v[64:65], off
	v_lshl_add_u64 v[64:65], v[10:11], 0, s[62:63]
	s_mov_b32 m0, s52
	v_mfma_f32_16x16x32_bf16 v[48:51], v[134:137], v[118:121], v[48:51]
	global_load_lds_dwordx4 v[64:65], off
	v_lshl_add_u64 v[64:65], v[12:13], 0, s[62:63]
	s_mov_b32 m0, s53
	s_nop 0
	global_load_lds_dwordx4 v[64:65], off
	v_lshl_add_u64 v[64:65], v[14:15], 0, s[62:63]
	s_mov_b32 m0, s54
	s_nop 0
	global_load_lds_dwordx4 v[64:65], off
	v_lshl_add_u64 v[64:65], v[16:17], 0, s[62:63]
	s_mov_b32 m0, s55
	s_nop 0
	global_load_lds_dwordx4 v[64:65], off
	ds_read_b128 v[122:125], v19 offset:16384
	ds_read_b128 v[118:121], v18
	ds_read_b128 v[126:129], v19 offset:18432
	ds_read_b128 v[130:133], v19 offset:20480
	ds_read_b128 v[134:137], v19 offset:22528
	s_waitcnt lgkmcnt(0)
	v_mfma_f32_16x16x32_bf16 v[28:31], v[122:125], v[118:121], v[28:31]
	v_lshl_add_u64 v[64:65], v[2:3], 0, s[94:95]
	s_mov_b32 m0, s56
	v_mfma_f32_16x16x32_bf16 v[36:39], v[126:129], v[118:121], v[36:39]
	v_mfma_f32_16x16x32_bf16 v[44:47], v[130:133], v[118:121], v[44:47]
	v_mfma_f32_16x16x32_bf16 v[24:27], v[134:137], v[118:121], v[24:27]
	ds_read_b128 v[118:121], v18 offset:2048
	s_waitcnt lgkmcnt(0)
	v_mfma_f32_16x16x32_bf16 v[56:59], v[122:125], v[118:121], v[56:59]
	v_mfma_f32_16x16x32_bf16 v[60:63], v[126:129], v[118:121], v[60:63]
	v_mfma_f32_16x16x32_bf16 v[94:97], v[130:133], v[118:121], v[94:97]
	v_mfma_f32_16x16x32_bf16 v[52:55], v[134:137], v[118:121], v[52:55]
	ds_read_b128 v[118:121], v18 offset:4096
	s_waitcnt lgkmcnt(0)
	v_mfma_f32_16x16x32_bf16 v[106:109], v[122:125], v[118:121], v[106:109]
	v_mfma_f32_16x16x32_bf16 v[110:113], v[126:129], v[118:121], v[110:113]
	v_mfma_f32_16x16x32_bf16 v[114:117], v[130:133], v[118:121], v[114:117]
	v_mfma_f32_16x16x32_bf16 v[98:101], v[134:137], v[118:121], v[98:101]
	ds_read_b128 v[118:121], v18 offset:6144
	s_waitcnt lgkmcnt(0)
	v_mfma_f32_16x16x32_bf16 v[20:23], v[122:125], v[118:121], v[20:23]
	ds_read_b128 v[122:125], v19 offset:17408
	v_mfma_f32_16x16x32_bf16 v[32:35], v[126:129], v[118:121], v[32:35]
	ds_read_b128 v[126:129], v19 offset:19456
	v_mfma_f32_16x16x32_bf16 v[40:43], v[130:133], v[118:121], v[40:43]
	ds_read_b128 v[130:133], v19 offset:21504
	v_mfma_f32_16x16x32_bf16 v[48:51], v[134:137], v[118:121], v[48:51]
	ds_read_b128 v[134:137], v19 offset:23552
	ds_read_b128 v[118:121], v18 offset:1024
	s_waitcnt lgkmcnt(0)
	v_mfma_f32_16x16x32_bf16 v[28:31], v[122:125], v[118:121], v[28:31]
	v_mfma_f32_16x16x32_bf16 v[36:39], v[126:129], v[118:121], v[36:39]
	v_mfma_f32_16x16x32_bf16 v[44:47], v[130:133], v[118:121], v[44:47]
	v_mfma_f32_16x16x32_bf16 v[24:27], v[134:137], v[118:121], v[24:27]
	ds_read_b128 v[118:121], v18 offset:3072
	s_waitcnt lgkmcnt(0)
	v_mfma_f32_16x16x32_bf16 v[56:59], v[122:125], v[118:121], v[56:59]
	v_mfma_f32_16x16x32_bf16 v[60:63], v[126:129], v[118:121], v[60:63]
	v_mfma_f32_16x16x32_bf16 v[94:97], v[130:133], v[118:121], v[94:97]
	v_mfma_f32_16x16x32_bf16 v[52:55], v[134:137], v[118:121], v[52:55]
	ds_read_b128 v[118:121], v18 offset:5120
	s_waitcnt lgkmcnt(0)
	v_mfma_f32_16x16x32_bf16 v[106:109], v[122:125], v[118:121], v[106:109]
	v_mfma_f32_16x16x32_bf16 v[110:113], v[126:129], v[118:121], v[110:113]
	v_mfma_f32_16x16x32_bf16 v[114:117], v[130:133], v[118:121], v[114:117]
	v_mfma_f32_16x16x32_bf16 v[98:101], v[134:137], v[118:121], v[98:101]
	ds_read_b128 v[118:121], v18 offset:7168
	s_waitcnt vmcnt(0)
	s_waitcnt lgkmcnt(0)
	s_barrier
	global_load_lds_dwordx4 v[64:65], off
	v_lshl_add_u64 v[64:65], v[4:5], 0, s[94:95]
	s_mov_b32 m0, s57
	s_waitcnt lgkmcnt(0)
	v_mfma_f32_16x16x32_bf16 v[20:23], v[122:125], v[118:121], v[20:23]
	global_load_lds_dwordx4 v[64:65], off
	v_lshl_add_u64 v[64:65], v[6:7], 0, s[94:95]
	s_mov_b32 m0, s58
	v_mfma_f32_16x16x32_bf16 v[32:35], v[126:129], v[118:121], v[32:35]
	global_load_lds_dwordx4 v[64:65], off
	v_lshl_add_u64 v[64:65], v[8:9], 0, s[94:95]
	s_mov_b32 m0, s59
	v_mfma_f32_16x16x32_bf16 v[40:43], v[130:133], v[118:121], v[40:43]
	global_load_lds_dwordx4 v[64:65], off
	v_lshl_add_u64 v[64:65], v[10:11], 0, s[94:95]
	s_mov_b32 m0, s60
	v_mfma_f32_16x16x32_bf16 v[48:51], v[134:137], v[118:121], v[48:51]
	global_load_lds_dwordx4 v[64:65], off
	v_lshl_add_u64 v[64:65], v[12:13], 0, s[94:95]
	s_mov_b32 m0, s61
	s_nop 0
	global_load_lds_dwordx4 v[64:65], off
	v_lshl_add_u64 v[64:65], v[14:15], 0, s[94:95]
	s_mov_b32 m0, s97
	s_nop 0
	global_load_lds_dwordx4 v[64:65], off
	v_lshl_add_u64 v[64:65], v[16:17], 0, s[94:95]
	s_mov_b32 m0, s44
	s_nop 0
	global_load_lds_dwordx4 v[64:65], off
	ds_read_b128 v[122:125], v19 offset:49152
	ds_read_b128 v[118:121], v18 offset:32768
	ds_read_b128 v[126:129], v19 offset:51200
	ds_read_b128 v[130:133], v19 offset:53248
	ds_read_b128 v[134:137], v19 offset:55296
	s_waitcnt lgkmcnt(0)
	v_mfma_f32_16x16x32_bf16 v[28:31], v[122:125], v[118:121], v[28:31]
	v_lshl_add_u64 v[64:65], v[2:3], 0, s[36:37]
	s_mov_b32 m0, s42
	v_mfma_f32_16x16x32_bf16 v[36:39], v[126:129], v[118:121], v[36:39]
	v_mfma_f32_16x16x32_bf16 v[44:47], v[130:133], v[118:121], v[44:47]
	v_mfma_f32_16x16x32_bf16 v[24:27], v[134:137], v[118:121], v[24:27]
	ds_read_b128 v[118:121], v18 offset:34816
	s_waitcnt lgkmcnt(0)
	v_mfma_f32_16x16x32_bf16 v[56:59], v[122:125], v[118:121], v[56:59]
	v_mfma_f32_16x16x32_bf16 v[60:63], v[126:129], v[118:121], v[60:63]
	v_mfma_f32_16x16x32_bf16 v[94:97], v[130:133], v[118:121], v[94:97]
	v_mfma_f32_16x16x32_bf16 v[52:55], v[134:137], v[118:121], v[52:55]
	ds_read_b128 v[118:121], v18 offset:36864
	s_waitcnt lgkmcnt(0)
	v_mfma_f32_16x16x32_bf16 v[106:109], v[122:125], v[118:121], v[106:109]
	v_mfma_f32_16x16x32_bf16 v[110:113], v[126:129], v[118:121], v[110:113]
	v_mfma_f32_16x16x32_bf16 v[114:117], v[130:133], v[118:121], v[114:117]
	v_mfma_f32_16x16x32_bf16 v[98:101], v[134:137], v[118:121], v[98:101]
	ds_read_b128 v[118:121], v18 offset:38912
	s_waitcnt lgkmcnt(0)
	v_mfma_f32_16x16x32_bf16 v[20:23], v[122:125], v[118:121], v[20:23]
	ds_read_b128 v[122:125], v19 offset:50176
	v_mfma_f32_16x16x32_bf16 v[32:35], v[126:129], v[118:121], v[32:35]
	ds_read_b128 v[126:129], v19 offset:52224
	v_mfma_f32_16x16x32_bf16 v[40:43], v[130:133], v[118:121], v[40:43]
	ds_read_b128 v[130:133], v19 offset:54272
	v_mfma_f32_16x16x32_bf16 v[48:51], v[134:137], v[118:121], v[48:51]
	ds_read_b128 v[134:137], v19 offset:56320
	ds_read_b128 v[118:121], v18 offset:33792
	s_waitcnt lgkmcnt(0)
	v_mfma_f32_16x16x32_bf16 v[28:31], v[122:125], v[118:121], v[28:31]
	v_mfma_f32_16x16x32_bf16 v[36:39], v[126:129], v[118:121], v[36:39]
	v_mfma_f32_16x16x32_bf16 v[44:47], v[130:133], v[118:121], v[44:47]
	v_mfma_f32_16x16x32_bf16 v[24:27], v[134:137], v[118:121], v[24:27]
	ds_read_b128 v[118:121], v18 offset:35840
	s_waitcnt lgkmcnt(0)
	v_mfma_f32_16x16x32_bf16 v[56:59], v[122:125], v[118:121], v[56:59]
	v_mfma_f32_16x16x32_bf16 v[60:63], v[126:129], v[118:121], v[60:63]
	v_mfma_f32_16x16x32_bf16 v[94:97], v[130:133], v[118:121], v[94:97]
	v_mfma_f32_16x16x32_bf16 v[52:55], v[134:137], v[118:121], v[52:55]
	ds_read_b128 v[118:121], v18 offset:37888
	s_waitcnt lgkmcnt(0)
	v_mfma_f32_16x16x32_bf16 v[106:109], v[122:125], v[118:121], v[106:109]
	v_mfma_f32_16x16x32_bf16 v[110:113], v[126:129], v[118:121], v[110:113]
	v_mfma_f32_16x16x32_bf16 v[114:117], v[130:133], v[118:121], v[114:117]
	v_mfma_f32_16x16x32_bf16 v[98:101], v[134:137], v[118:121], v[98:101]
	ds_read_b128 v[118:121], v18 offset:39936
	s_waitcnt vmcnt(0)
	s_waitcnt lgkmcnt(0)
	s_barrier
	global_load_lds_dwordx4 v[64:65], off
	v_lshl_add_u64 v[64:65], v[4:5], 0, s[36:37]
	s_mov_b32 m0, s43
	s_waitcnt lgkmcnt(0)
	v_mfma_f32_16x16x32_bf16 v[20:23], v[122:125], v[118:121], v[20:23]
	global_load_lds_dwordx4 v[64:65], off
	v_lshl_add_u64 v[64:65], v[6:7], 0, s[36:37]
	s_mov_b32 m0, s50
	v_mfma_f32_16x16x32_bf16 v[32:35], v[126:129], v[118:121], v[32:35]
	global_load_lds_dwordx4 v[64:65], off
	v_lshl_add_u64 v[64:65], v[8:9], 0, s[36:37]
	s_mov_b32 m0, s51
	v_mfma_f32_16x16x32_bf16 v[40:43], v[130:133], v[118:121], v[40:43]
	global_load_lds_dwordx4 v[64:65], off
	v_lshl_add_u64 v[64:65], v[10:11], 0, s[36:37]
	s_mov_b32 m0, s52
	v_mfma_f32_16x16x32_bf16 v[48:51], v[134:137], v[118:121], v[48:51]
	global_load_lds_dwordx4 v[64:65], off
	v_lshl_add_u64 v[64:65], v[12:13], 0, s[36:37]
	s_mov_b32 m0, s53
	s_nop 0
	global_load_lds_dwordx4 v[64:65], off
	v_lshl_add_u64 v[64:65], v[14:15], 0, s[36:37]
	s_mov_b32 m0, s54
	s_nop 0
	global_load_lds_dwordx4 v[64:65], off
	v_lshl_add_u64 v[64:65], v[16:17], 0, s[36:37]
	s_mov_b32 m0, s55
	s_nop 0
	global_load_lds_dwordx4 v[64:65], off
	ds_read_b128 v[122:125], v19 offset:16384
	ds_read_b128 v[118:121], v18
	ds_read_b128 v[126:129], v19 offset:18432
	ds_read_b128 v[130:133], v19 offset:20480
	ds_read_b128 v[134:137], v19 offset:22528
	s_waitcnt lgkmcnt(0)
	v_mfma_f32_16x16x32_bf16 v[28:31], v[122:125], v[118:121], v[28:31]
	v_lshl_add_u64 v[64:65], v[2:3], 0, s[22:23]
	s_mov_b32 m0, s56
	v_lshl_add_u64 v[2:3], v[2:3], 0, s[26:27]
	v_mfma_f32_16x16x32_bf16 v[36:39], v[126:129], v[118:121], v[36:39]
	v_mfma_f32_16x16x32_bf16 v[44:47], v[130:133], v[118:121], v[44:47]
	v_mfma_f32_16x16x32_bf16 v[24:27], v[134:137], v[118:121], v[24:27]
	ds_read_b128 v[118:121], v18 offset:2048
	s_waitcnt lgkmcnt(0)
	v_mfma_f32_16x16x32_bf16 v[56:59], v[122:125], v[118:121], v[56:59]
	v_mfma_f32_16x16x32_bf16 v[60:63], v[126:129], v[118:121], v[60:63]
	v_mfma_f32_16x16x32_bf16 v[94:97], v[130:133], v[118:121], v[94:97]
	v_mfma_f32_16x16x32_bf16 v[52:55], v[134:137], v[118:121], v[52:55]
	ds_read_b128 v[118:121], v18 offset:4096
	s_waitcnt lgkmcnt(0)
	v_mfma_f32_16x16x32_bf16 v[106:109], v[122:125], v[118:121], v[106:109]
	v_mfma_f32_16x16x32_bf16 v[110:113], v[126:129], v[118:121], v[110:113]
	v_mfma_f32_16x16x32_bf16 v[114:117], v[130:133], v[118:121], v[114:117]
	v_mfma_f32_16x16x32_bf16 v[98:101], v[134:137], v[118:121], v[98:101]
	ds_read_b128 v[118:121], v18 offset:6144
	s_waitcnt lgkmcnt(0)
	v_mfma_f32_16x16x32_bf16 v[20:23], v[122:125], v[118:121], v[20:23]
	ds_read_b128 v[122:125], v19 offset:17408
	v_mfma_f32_16x16x32_bf16 v[32:35], v[126:129], v[118:121], v[32:35]
	ds_read_b128 v[126:129], v19 offset:19456
	v_mfma_f32_16x16x32_bf16 v[40:43], v[130:133], v[118:121], v[40:43]
	ds_read_b128 v[130:133], v19 offset:21504
	v_mfma_f32_16x16x32_bf16 v[48:51], v[134:137], v[118:121], v[48:51]
	ds_read_b128 v[134:137], v19 offset:23552
	ds_read_b128 v[118:121], v18 offset:1024
	s_waitcnt lgkmcnt(0)
	v_mfma_f32_16x16x32_bf16 v[28:31], v[122:125], v[118:121], v[28:31]
	v_mfma_f32_16x16x32_bf16 v[36:39], v[126:129], v[118:121], v[36:39]
	v_mfma_f32_16x16x32_bf16 v[44:47], v[130:133], v[118:121], v[44:47]
	v_mfma_f32_16x16x32_bf16 v[24:27], v[134:137], v[118:121], v[24:27]
	ds_read_b128 v[118:121], v18 offset:3072
	s_waitcnt lgkmcnt(0)
	v_mfma_f32_16x16x32_bf16 v[56:59], v[122:125], v[118:121], v[56:59]
	v_mfma_f32_16x16x32_bf16 v[60:63], v[126:129], v[118:121], v[60:63]
	v_mfma_f32_16x16x32_bf16 v[94:97], v[130:133], v[118:121], v[94:97]
	v_mfma_f32_16x16x32_bf16 v[52:55], v[134:137], v[118:121], v[52:55]
	ds_read_b128 v[118:121], v18 offset:5120
	s_waitcnt lgkmcnt(0)
	v_mfma_f32_16x16x32_bf16 v[106:109], v[122:125], v[118:121], v[106:109]
	v_mfma_f32_16x16x32_bf16 v[110:113], v[126:129], v[118:121], v[110:113]
	v_mfma_f32_16x16x32_bf16 v[114:117], v[130:133], v[118:121], v[114:117]
	v_mfma_f32_16x16x32_bf16 v[98:101], v[134:137], v[118:121], v[98:101]
	ds_read_b128 v[118:121], v18 offset:7168
	s_waitcnt vmcnt(0)
	s_waitcnt lgkmcnt(0)
	s_barrier
	global_load_lds_dwordx4 v[64:65], off
	v_lshl_add_u64 v[64:65], v[4:5], 0, s[22:23]
	s_mov_b32 m0, s57
	s_waitcnt lgkmcnt(0)
	v_mfma_f32_16x16x32_bf16 v[20:23], v[122:125], v[118:121], v[20:23]
	global_load_lds_dwordx4 v[64:65], off
	v_lshl_add_u64 v[64:65], v[6:7], 0, s[22:23]
	s_mov_b32 m0, s58
	v_mfma_f32_16x16x32_bf16 v[32:35], v[126:129], v[118:121], v[32:35]
	global_load_lds_dwordx4 v[64:65], off
	v_lshl_add_u64 v[64:65], v[8:9], 0, s[22:23]
	s_mov_b32 m0, s59
	v_mfma_f32_16x16x32_bf16 v[40:43], v[130:133], v[118:121], v[40:43]
	global_load_lds_dwordx4 v[64:65], off
	v_lshl_add_u64 v[64:65], v[10:11], 0, s[22:23]
	s_mov_b32 m0, s60
	v_mfma_f32_16x16x32_bf16 v[48:51], v[134:137], v[118:121], v[48:51]
	global_load_lds_dwordx4 v[64:65], off
	v_lshl_add_u64 v[64:65], v[12:13], 0, s[22:23]
	s_mov_b32 m0, s61
	s_nop 0
	global_load_lds_dwordx4 v[64:65], off
	v_lshl_add_u64 v[64:65], v[14:15], 0, s[22:23]
	s_mov_b32 m0, s97
	s_nop 0
	global_load_lds_dwordx4 v[64:65], off
	v_lshl_add_u64 v[64:65], v[16:17], 0, s[22:23]
	s_mov_b32 m0, s44
	s_mov_b32 s44, 7
	global_load_lds_dwordx4 v[64:65], off
	ds_read_b128 v[122:125], v19 offset:49152
	ds_read_b128 v[118:121], v18 offset:32768
	ds_read_b128 v[126:129], v19 offset:51200
	ds_read_b128 v[130:133], v19 offset:53248
	ds_read_b128 v[134:137], v19 offset:55296
	s_waitcnt lgkmcnt(0)
	v_mfma_f32_16x16x32_bf16 v[28:31], v[122:125], v[118:121], v[28:31]
	s_mov_b32 m0, s42
	v_mfma_f32_16x16x32_bf16 v[36:39], v[126:129], v[118:121], v[36:39]
	v_mfma_f32_16x16x32_bf16 v[44:47], v[130:133], v[118:121], v[44:47]
	v_mfma_f32_16x16x32_bf16 v[24:27], v[134:137], v[118:121], v[24:27]
	ds_read_b128 v[118:121], v18 offset:34816
	s_waitcnt lgkmcnt(0)
	v_mfma_f32_16x16x32_bf16 v[56:59], v[122:125], v[118:121], v[56:59]
	v_mfma_f32_16x16x32_bf16 v[60:63], v[126:129], v[118:121], v[60:63]
	v_mfma_f32_16x16x32_bf16 v[94:97], v[130:133], v[118:121], v[94:97]
	v_mfma_f32_16x16x32_bf16 v[52:55], v[134:137], v[118:121], v[52:55]
	ds_read_b128 v[118:121], v18 offset:36864
	s_waitcnt lgkmcnt(0)
	v_mfma_f32_16x16x32_bf16 v[106:109], v[122:125], v[118:121], v[106:109]
	v_mfma_f32_16x16x32_bf16 v[110:113], v[126:129], v[118:121], v[110:113]
	v_mfma_f32_16x16x32_bf16 v[114:117], v[130:133], v[118:121], v[114:117]
	v_mfma_f32_16x16x32_bf16 v[98:101], v[134:137], v[118:121], v[98:101]
	ds_read_b128 v[118:121], v18 offset:38912
	s_waitcnt lgkmcnt(0)
	v_mfma_f32_16x16x32_bf16 v[20:23], v[122:125], v[118:121], v[20:23]
	ds_read_b128 v[122:125], v19 offset:50176
	v_mfma_f32_16x16x32_bf16 v[32:35], v[126:129], v[118:121], v[32:35]
	ds_read_b128 v[126:129], v19 offset:52224
	v_mfma_f32_16x16x32_bf16 v[40:43], v[130:133], v[118:121], v[40:43]
	ds_read_b128 v[130:133], v19 offset:54272
	v_mfma_f32_16x16x32_bf16 v[48:51], v[134:137], v[118:121], v[48:51]
	ds_read_b128 v[134:137], v19 offset:56320
	ds_read_b128 v[118:121], v18 offset:33792
	s_waitcnt lgkmcnt(0)
	v_mfma_f32_16x16x32_bf16 v[28:31], v[122:125], v[118:121], v[28:31]
	v_mfma_f32_16x16x32_bf16 v[36:39], v[126:129], v[118:121], v[36:39]
	v_mfma_f32_16x16x32_bf16 v[44:47], v[130:133], v[118:121], v[44:47]
	v_mfma_f32_16x16x32_bf16 v[24:27], v[134:137], v[118:121], v[24:27]
	ds_read_b128 v[118:121], v18 offset:35840
	s_waitcnt lgkmcnt(0)
	v_mfma_f32_16x16x32_bf16 v[56:59], v[122:125], v[118:121], v[56:59]
	v_mfma_f32_16x16x32_bf16 v[60:63], v[126:129], v[118:121], v[60:63]
	v_mfma_f32_16x16x32_bf16 v[94:97], v[130:133], v[118:121], v[94:97]
	v_mfma_f32_16x16x32_bf16 v[52:55], v[134:137], v[118:121], v[52:55]
	ds_read_b128 v[118:121], v18 offset:37888
	s_waitcnt lgkmcnt(0)
	v_mfma_f32_16x16x32_bf16 v[106:109], v[122:125], v[118:121], v[106:109]
	v_mfma_f32_16x16x32_bf16 v[110:113], v[126:129], v[118:121], v[110:113]
	v_mfma_f32_16x16x32_bf16 v[114:117], v[130:133], v[118:121], v[114:117]
	v_mfma_f32_16x16x32_bf16 v[98:101], v[134:137], v[118:121], v[98:101]
	ds_read_b128 v[118:121], v18 offset:39936
	s_waitcnt vmcnt(0)
	s_waitcnt lgkmcnt(0)
	s_barrier
	global_load_lds_dwordx4 v[2:3], off
	v_lshl_add_u64 v[2:3], v[4:5], 0, s[26:27]
	s_mov_b32 m0, s43
	s_waitcnt lgkmcnt(0)
	v_mfma_f32_16x16x32_bf16 v[20:23], v[122:125], v[118:121], v[20:23]
	global_load_lds_dwordx4 v[2:3], off
	v_lshl_add_u64 v[2:3], v[6:7], 0, s[26:27]
	s_mov_b32 m0, s50
	v_mfma_f32_16x16x32_bf16 v[32:35], v[126:129], v[118:121], v[32:35]
	global_load_lds_dwordx4 v[2:3], off
	v_lshl_add_u64 v[2:3], v[8:9], 0, s[26:27]
	s_mov_b32 m0, s51
	v_mfma_f32_16x16x32_bf16 v[6:9], v[134:137], v[118:121], v[48:51]
	global_load_lds_dwordx4 v[2:3], off
	v_lshl_add_u64 v[2:3], v[10:11], 0, s[26:27]
	s_mov_b32 m0, s52
	v_mfma_f32_16x16x32_bf16 v[40:43], v[130:133], v[118:121], v[40:43]
	global_load_lds_dwordx4 v[2:3], off
	v_lshl_add_u64 v[2:3], v[12:13], 0, s[26:27]
	s_mov_b32 m0, s53
	s_mov_b32 s50, 0x40000
	global_load_lds_dwordx4 v[2:3], off
	v_lshl_add_u64 v[2:3], v[14:15], 0, s[26:27]
	s_mov_b32 m0, s54
	s_mov_b64 s[42:43], 0
	global_load_lds_dwordx4 v[2:3], off
	v_lshl_add_u64 v[2:3], v[16:17], 0, s[26:27]
	s_mov_b32 m0, s55
	s_movk_i32 s51, 0x200
	global_load_lds_dwordx4 v[2:3], off
	ds_read_b128 v[156:159], v19 offset:16384
	ds_read_b128 v[160:163], v18
	ds_read_b128 v[138:141], v19 offset:18432
	ds_read_b128 v[164:167], v19 offset:20480
	ds_read_b128 v[168:171], v19 offset:19456
	ds_read_b128 v[234:237], v19 offset:22528
	ds_read_b128 v[238:241], v19 offset:21504
	ds_read_b128 v[250:253], v19 offset:17408
	s_nop 0
	s_nop 0
	s_nop 0
	s_waitcnt lgkmcnt(6)
	v_mfma_f32_16x16x32_bf16 v[14:17], v[156:159], v[160:163], v[28:31]
	s_nop 2
	s_nop 0
	s_nop 0
	s_nop 0
	s_nop 0
	s_waitcnt lgkmcnt(4)
	v_mfma_f32_16x16x32_bf16 v[118:121], v[164:167], v[160:163], v[44:47]
	s_nop 2
	s_nop 0
	s_nop 0
	s_nop 0
	v_mfma_f32_16x16x32_bf16 v[36:39], v[138:141], v[160:163], v[36:39]
	s_nop 0
	s_waitcnt lgkmcnt(2)
	v_mfma_f32_16x16x32_bf16 v[10:13], v[234:237], v[160:163], v[24:27]
	ds_read_b128 v[160:163], v18 offset:2048
	s_nop 2
	s_nop 0
	s_nop 0
	s_waitcnt lgkmcnt(0)
	v_mfma_f32_16x16x32_bf16 v[122:125], v[156:159], v[160:163], v[56:59]
	v_mfma_f32_16x16x32_bf16 v[126:129], v[138:141], v[160:163], v[60:63]
	v_mfma_f32_16x16x32_bf16 v[94:97], v[164:167], v[160:163], v[94:97]
	v_mfma_f32_16x16x32_bf16 v[24:27], v[234:237], v[160:163], v[52:55]
	ds_read_b128 v[160:163], v18 offset:4096
	s_nop 2
	s_nop 0
	s_nop 0
	s_waitcnt lgkmcnt(0)
	v_mfma_f32_16x16x32_bf16 v[106:109], v[156:159], v[160:163], v[106:109]
	v_mfma_f32_16x16x32_bf16 v[110:113], v[138:141], v[160:163], v[110:113]
	v_mfma_f32_16x16x32_bf16 v[114:117], v[164:167], v[160:163], v[114:117]
	v_mfma_f32_16x16x32_bf16 v[98:101], v[234:237], v[160:163], v[98:101]
	ds_read_b128 v[160:163], v18 offset:6144
	s_nop 0
	s_nop 0
	s_waitcnt lgkmcnt(0)
	v_mfma_f32_16x16x32_bf16 v[152:155], v[234:237], v[160:163], v[6:9]
	ds_read_b128 v[234:237], v18 offset:1024
	s_nop 2
	s_nop 0
	s_nop 0
	s_waitcnt lgkmcnt(0)
	v_mfma_f32_16x16x32_bf16 v[58:61], v[238:241], v[234:237], v[118:121]
	s_nop 2
	s_nop 0
	v_mfma_f32_16x16x32_bf16 v[2:5], v[156:159], v[160:163], v[20:23]
	ds_read_b128 v[156:159], v19 offset:23552
	v_mfma_f32_16x16x32_bf16 v[130:133], v[138:141], v[160:163], v[32:35]
	ds_read_b128 v[138:141], v18 offset:3072
	v_mfma_f32_16x16x32_bf16 v[134:137], v[164:167], v[160:163], v[40:43]
	ds_read_b128 v[164:167], v18 offset:5120
	ds_read_b128 v[160:163], v18 offset:7168
	v_mfma_f32_16x16x32_bf16 v[46:49], v[250:253], v[234:237], v[14:17]
	v_mfma_f32_16x16x32_bf16 v[50:53], v[168:171], v[234:237], v[36:39]
	s_nop 0
	s_waitcnt lgkmcnt(3)
	v_mfma_f32_16x16x32_bf16 v[62:65], v[156:159], v[234:237], v[10:13]
	s_nop 0
	s_nop 0
	s_waitcnt lgkmcnt(2)
	v_mfma_f32_16x16x32_bf16 v[54:57], v[250:253], v[138:141], v[122:125]
	v_mfma_f32_16x16x32_bf16 v[34:37], v[168:171], v[138:141], v[126:129]
	v_mfma_f32_16x16x32_bf16 v[30:33], v[238:241], v[138:141], v[94:97]
	v_mfma_f32_16x16x32_bf16 v[22:25], v[156:159], v[138:141], v[24:27]
	s_nop 0
	s_nop 0
	v_lshl_add_u64 v[94:95], v[86:87], 0, s[2:3]
	v_lshl_add_u64 v[96:97], v[88:89], 0, s[2:3]
	s_nop 0
	s_waitcnt lgkmcnt(1)
	v_mfma_f32_16x16x32_bf16 v[38:41], v[250:253], v[164:167], v[106:109]
	s_nop 2
	s_nop 0
	v_mfma_f32_16x16x32_bf16 v[14:17], v[168:171], v[164:167], v[110:113]
	v_mfma_f32_16x16x32_bf16 v[10:13], v[238:241], v[164:167], v[114:117]
	v_mfma_f32_16x16x32_bf16 v[6:9], v[156:159], v[164:167], v[98:101]
	s_nop 0
	s_waitcnt lgkmcnt(0)
	v_mfma_f32_16x16x32_bf16 v[42:45], v[250:253], v[160:163], v[2:5]
	s_nop 0
	v_lshl_add_u64 v[98:99], v[90:91], 0, s[2:3]
	v_lshl_add_u64 v[100:101], v[92:93], 0, s[2:3]
	v_mfma_f32_16x16x32_bf16 v[18:21], v[168:171], v[160:163], v[130:133]
	v_mfma_f32_16x16x32_bf16 v[26:29], v[238:241], v[160:163], v[134:137]
	v_mfma_f32_16x16x32_bf16 v[2:5], v[156:159], v[160:163], v[152:155]
	s_branch .LBB0_63
	.p2align 8
